# GEMM accumulator zeroing with 64 v_mov_b64 instead of 128 v_mov_b32 per unit
# baseline (speedup 1.0000x reference)
; template <class Epi, class Sched, bool ALIGN_EPI = true, bool SP2 = true, bool GS = false>
; __device__ __forceinline__ void gemm_phase(PG8_LAS unsigned char* lds, const Gemm g, const Sched& S, const Epi& E, const float* gs_ss = nullptr) {
;     ...
; #pragma unroll
;         for (int a = 0; a < 2; ++a)
; #pragma unroll
;             for (int b = 0; b < 2; ++b)
; #pragma unroll
;                 for (int m = 0; m < 4; ++m)
; #pragma unroll
;                     for (int n = 0; n < 2; ++n) acc[a][b][m][n] = (f32x4){0.f, 0.f, 0.f, 0.f};
;         cur = nxt; cA = nA; cB = nB; ++ui;
.LBB0_150:
	s_ashr_i32 s53, s52, 31
	s_lshl_b64 s[2:3], s[52:53], 20
	s_add_u32 s54, s16, s2
	s_addc_u32 s55, s17, s3
	s_and_b64 s[2:3], s[38:39], exec
	s_cselect_b32 s13, s55, s41
	s_cselect_b32 s53, s54, s40
	s_ashr_i32 s51, s50, 31
	s_lshl_b64 s[2:3], s[50:51], 20
	s_add_u32 s56, s18, s2
	s_addc_u32 s57, s22, s3
	s_and_b64 s[2:3], s[38:39], exec
	s_cselect_b32 s51, s57, s43
	s_cselect_b32 s64, s56, s42
	s_add_u32 s40, s40, 0x80080
	s_addc_u32 s41, s41, 0
	s_add_u32 s42, s42, 0x100
	v_mov_b64_e32 v[2:3], 0
	s_addc_u32 s43, s43, 0
	s_mov_b32 s65, -2
	v_mov_b64_e32 v[4:5], 0
	v_mov_b64_e32 v[6:7], 0
	v_mov_b64_e32 v[8:9], 0
	v_mov_b64_e32 v[10:11], 0
	v_mov_b64_e32 v[12:13], 0
	v_mov_b64_e32 v[14:15], 0
	v_mov_b64_e32 v[16:17], 0
	v_mov_b64_e32 v[18:19], 0
	v_mov_b64_e32 v[20:21], 0
	v_mov_b64_e32 v[22:23], 0
	v_mov_b64_e32 v[24:25], 0
	v_mov_b64_e32 v[26:27], 0
	v_mov_b64_e32 v[28:29], 0
	v_mov_b64_e32 v[30:31], 0
	v_mov_b64_e32 v[32:33], 0
	v_mov_b64_e32 v[34:35], 0
	v_mov_b64_e32 v[36:37], 0
	v_mov_b64_e32 v[38:39], 0
	v_mov_b64_e32 v[40:41], 0
	v_mov_b64_e32 v[42:43], 0
	v_mov_b64_e32 v[44:45], 0
	v_mov_b64_e32 v[46:47], 0
	v_mov_b64_e32 v[48:49], 0
	v_mov_b64_e32 v[50:51], 0
	v_mov_b64_e32 v[52:53], 0
	v_mov_b64_e32 v[54:55], 0
	v_mov_b64_e32 v[56:57], 0
	v_mov_b64_e32 v[58:59], 0
	v_mov_b64_e32 v[60:61], 0
	v_mov_b64_e32 v[62:63], 0
	v_mov_b64_e32 v[64:65], 0
	v_mov_b64_e32 v[66:67], 0
	v_mov_b64_e32 v[68:69], 0
	v_mov_b64_e32 v[70:71], 0
	v_mov_b64_e32 v[72:73], 0
	v_mov_b64_e32 v[74:75], 0
	v_mov_b64_e32 v[76:77], 0
	v_mov_b64_e32 v[78:79], 0
	v_mov_b64_e32 v[80:81], 0
	v_mov_b64_e32 v[82:83], 0
	v_mov_b64_e32 v[84:85], 0
	v_mov_b64_e32 v[86:87], 0
	v_mov_b64_e32 v[88:89], 0
	v_mov_b64_e32 v[90:91], 0
	v_mov_b64_e32 v[92:93], 0
	v_mov_b64_e32 v[94:95], 0
	v_mov_b64_e32 v[96:97], 0
	v_mov_b64_e32 v[98:99], 0
	v_mov_b64_e32 v[100:101], 0
	v_mov_b64_e32 v[102:103], 0
	v_mov_b64_e32 v[104:105], 0
	v_mov_b64_e32 v[106:107], 0
	v_mov_b64_e32 v[108:109], 0
	v_mov_b64_e32 v[110:111], 0
	v_mov_b64_e32 v[112:113], 0
	v_mov_b64_e32 v[114:115], 0
	v_mov_b64_e32 v[116:117], 0
	v_mov_b64_e32 v[118:119], 0
	v_mov_b64_e32 v[120:121], 0
	v_mov_b64_e32 v[122:123], 0
	v_mov_b64_e32 v[124:125], 0
	v_mov_b64_e32 v[126:127], 0
	v_mov_b64_e32 v[128:129], 0

; template <class Epi, class Sched, bool ALIGN_EPI = true, bool SP2 = true, bool GS = false>
; __device__ __forceinline__ void gemm_phase(PG8_LAS unsigned char* lds, const Gemm g, const Sched& S, const Epi& E, const float* gs_ss = nullptr) {
;     ...
; #pragma unroll
;         for (int a = 0; a < 2; ++a)
; #pragma unroll
;             for (int b = 0; b < 2; ++b)
; #pragma unroll
;                 for (int m = 0; m < 4; ++m)
; #pragma unroll
;                     for (int n = 0; n < 2; ++n) acc[a][b][m][n] = (f32x4){0.f, 0.f, 0.f, 0.f};
;         cur = nxt; cA = nA; cB = nB; ++ui;
.LBB0_313:
	s_ashr_i32 s51, s50, 31
	s_lshl_b64 s[2:3], s[50:51], 20
	s_cmp_gt_i32 s48, 13
	s_cselect_b32 s13, 0xd8c0000, 0
	s_cselect_b32 s17, 0x5200000, 0
	s_add_u32 s13, s18, s13
	s_addc_u32 s16, s22, 0
	s_add_u32 s54, s13, s2
	s_addc_u32 s55, s16, s3
	s_and_b64 s[2:3], s[52:53], exec
	s_cselect_b32 s13, s55, s39
	s_cselect_b32 s16, s54, s38
	s_add_u32 s17, s8, s17
	s_addc_u32 s20, s9, 0
	s_ashr_i32 s49, s48, 31
	s_lshl_b64 s[2:3], s[48:49], 20
	s_add_u32 s56, s17, s2
	s_addc_u32 s57, s20, s3
	s_and_b64 s[2:3], s[52:53], exec
	s_cselect_b32 s17, s57, s41
	s_cselect_b32 s49, s56, s40
	s_add_u32 s38, s38, 0x80080
	s_addc_u32 s39, s39, 0
	s_add_u32 s40, s40, 0x100
	v_mov_b64_e32 v[2:3], 0
	s_addc_u32 s41, s41, 0
	s_mov_b32 s51, -2
	v_mov_b64_e32 v[4:5], 0
	v_mov_b64_e32 v[6:7], 0
	v_mov_b64_e32 v[8:9], 0
	v_mov_b64_e32 v[10:11], 0
	v_mov_b64_e32 v[12:13], 0
	v_mov_b64_e32 v[14:15], 0
	v_mov_b64_e32 v[16:17], 0
	v_mov_b64_e32 v[18:19], 0
	v_mov_b64_e32 v[20:21], 0
	v_mov_b64_e32 v[22:23], 0
	v_mov_b64_e32 v[24:25], 0
	v_mov_b64_e32 v[26:27], 0
	v_mov_b64_e32 v[28:29], 0
	v_mov_b64_e32 v[30:31], 0
	v_mov_b64_e32 v[32:33], 0
	v_mov_b64_e32 v[34:35], 0
	v_mov_b64_e32 v[36:37], 0
	v_mov_b64_e32 v[38:39], 0
	v_mov_b64_e32 v[40:41], 0
	v_mov_b64_e32 v[42:43], 0
	v_mov_b64_e32 v[44:45], 0
	v_mov_b64_e32 v[46:47], 0
	v_mov_b64_e32 v[48:49], 0
	v_mov_b64_e32 v[50:51], 0
	v_mov_b64_e32 v[52:53], 0
	v_mov_b64_e32 v[54:55], 0
	v_mov_b64_e32 v[56:57], 0
	v_mov_b64_e32 v[58:59], 0
	v_mov_b64_e32 v[60:61], 0
	v_mov_b64_e32 v[62:63], 0
	v_mov_b64_e32 v[64:65], 0
	v_mov_b64_e32 v[66:67], 0
	v_mov_b64_e32 v[68:69], 0
	v_mov_b64_e32 v[70:71], 0
	v_mov_b64_e32 v[72:73], 0
	v_mov_b64_e32 v[74:75], 0
	v_mov_b64_e32 v[76:77], 0
	v_mov_b64_e32 v[78:79], 0
	v_mov_b64_e32 v[80:81], 0
	v_mov_b64_e32 v[82:83], 0
	v_mov_b64_e32 v[84:85], 0
	v_mov_b64_e32 v[86:87], 0
	v_mov_b64_e32 v[88:89], 0
	v_mov_b64_e32 v[90:91], 0
	v_mov_b64_e32 v[92:93], 0
	v_mov_b64_e32 v[94:95], 0
	v_mov_b64_e32 v[96:97], 0
	v_mov_b64_e32 v[98:99], 0
	v_mov_b64_e32 v[100:101], 0
	v_mov_b64_e32 v[102:103], 0
	v_mov_b64_e32 v[104:105], 0
	v_mov_b64_e32 v[106:107], 0
	v_mov_b64_e32 v[108:109], 0
	v_mov_b64_e32 v[110:111], 0
	v_mov_b64_e32 v[112:113], 0
	v_mov_b64_e32 v[114:115], 0
	v_mov_b64_e32 v[116:117], 0
	v_mov_b64_e32 v[118:119], 0
	v_mov_b64_e32 v[120:121], 0
	v_mov_b64_e32 v[122:123], 0
	v_mov_b64_e32 v[124:125], 0
	v_mov_b64_e32 v[126:127], 0
	v_mov_b64_e32 v[128:129], 0

; template <class Epi, class Sched, bool ALIGN_EPI = true, bool SP2 = true, bool GS = false>
; __device__ __forceinline__ void gemm_phase(PG8_LAS unsigned char* lds, const Gemm g, const Sched& S, const Epi& E, const float* gs_ss = nullptr) {
;     ...
; #pragma unroll
;         for (int a = 0; a < 2; ++a)
; #pragma unroll
;             for (int b = 0; b < 2; ++b)
; #pragma unroll
;                 for (int m = 0; m < 4; ++m)
; #pragma unroll
;                     for (int n = 0; n < 2; ++n) acc[a][b][m][n] = (f32x4){0.f, 0.f, 0.f, 0.f};
;         cur = nxt; cA = nA; cB = nB; ++ui;
.LBB0_787:
	s_ashr_i32 s8, s12, 1
	s_ashr_i32 s9, s8, 31
	s_lshl_b64 s[8:9], s[8:9], 23
	s_add_u32 s13, s44, s8
	s_addc_u32 s16, s45, s9
	s_ashr_i32 s57, s56, 31
	s_lshl_b64 s[8:9], s[56:57], 18
	s_add_u32 s60, s13, s8
	s_addc_u32 s61, s16, s9
	s_and_b64 s[8:9], s[62:63], exec
	s_cselect_b32 s16, s61, s3
	s_cselect_b32 s17, s60, s2
	s_ashr_i32 s13, s12, 31
	s_lshl_b64 s[8:9], s[12:13], 18
	s_add_u32 s8, s23, s8
	s_addc_u32 s9, s24, s9
	s_and_b64 s[20:21], s[62:63], exec
	s_cselect_b32 s13, s9, s41
	s_cselect_b32 s18, s8, s40
	s_add_u32 s34, s2, 0x20080
	s_addc_u32 s35, s3, 0
	s_add_u32 s29, s40, 0x100
	s_waitcnt lgkmcnt(0)
	v_mov_b64_e32 v[2:3], 0
	s_addc_u32 s40, s41, 0
	s_mov_b32 s41, -2
	v_mov_b64_e32 v[4:5], 0
	v_mov_b64_e32 v[6:7], 0
	v_mov_b64_e32 v[8:9], 0
	v_mov_b64_e32 v[10:11], 0
	v_mov_b64_e32 v[12:13], 0
	v_mov_b64_e32 v[14:15], 0
	v_mov_b64_e32 v[16:17], 0
	v_mov_b64_e32 v[22:23], 0
	v_mov_b64_e32 v[24:25], 0
	v_mov_b64_e32 v[34:35], 0
	v_mov_b64_e32 v[36:37], 0
	v_mov_b64_e32 v[50:51], 0
	v_mov_b64_e32 v[52:53], 0
	v_mov_b64_e32 v[54:55], 0
	v_mov_b64_e32 v[56:57], 0
	v_mov_b64_e32 v[62:63], 0
	v_mov_b64_e32 v[64:65], 0
	v_mov_b64_e32 v[66:67], 0
	v_mov_b64_e32 v[68:69], 0
	v_mov_b64_e32 v[74:75], 0
	v_mov_b64_e32 v[76:77], 0
	v_mov_b64_e32 v[78:79], 0
	v_mov_b64_e32 v[80:81], 0
	v_mov_b64_e32 v[86:87], 0
	v_mov_b64_e32 v[88:89], 0
	v_mov_b64_e32 v[90:91], 0
	v_mov_b64_e32 v[92:93], 0
	v_mov_b64_e32 v[98:99], 0
	v_mov_b64_e32 v[100:101], 0
	v_mov_b64_e32 v[102:103], 0
	v_mov_b64_e32 v[104:105], 0
	v_mov_b64_e32 v[110:111], 0
	v_mov_b64_e32 v[112:113], 0
	v_mov_b64_e32 v[114:115], 0
	v_mov_b64_e32 v[116:117], 0
	v_mov_b64_e32 v[122:123], 0
	v_mov_b64_e32 v[124:125], 0
	v_mov_b64_e32 v[126:127], 0
	v_mov_b64_e32 v[128:129], 0
	v_mov_b64_e32 v[130:131], 0
	v_mov_b64_e32 v[132:133], 0
	v_mov_b64_e32 v[134:135], 0
	v_mov_b64_e32 v[136:137], 0
	v_mov_b64_e32 v[138:139], 0
	v_mov_b64_e32 v[140:141], 0
	v_mov_b64_e32 v[142:143], 0
	v_mov_b64_e32 v[144:145], 0
	v_mov_b64_e32 v[146:147], 0
	v_mov_b64_e32 v[148:149], 0
	v_mov_b64_e32 v[150:151], 0
	v_mov_b64_e32 v[152:153], 0
	v_mov_b64_e32 v[154:155], 0
	v_mov_b64_e32 v[156:157], 0
	v_mov_b64_e32 v[158:159], 0
	v_mov_b64_e32 v[160:161], 0
	v_mov_b64_e32 v[162:163], 0
	v_mov_b64_e32 v[164:165], 0
	v_mov_b64_e32 v[166:167], 0
	v_mov_b64_e32 v[168:169], 0
	v_mov_b64_e32 v[170:171], 0
	v_mov_b64_e32 v[172:173], 0
	v_mov_b64_e32 v[174:175], 0
	v_mov_b64_e32 v[176:177], 0

; template <class Epi, class Sched, bool ALIGN_EPI = true, bool SP2 = true, bool GS = false>
; __device__ __forceinline__ void gemm_phase(PG8_LAS unsigned char* lds, const Gemm g, const Sched& S, const Epi& E, const float* gs_ss = nullptr) {
;     ...
; #pragma unroll
;         for (int a = 0; a < 2; ++a)
; #pragma unroll
;             for (int b = 0; b < 2; ++b)
; #pragma unroll
;                 for (int m = 0; m < 4; ++m)
; #pragma unroll
;                     for (int n = 0; n < 2; ++n) acc[a][b][m][n] = (f32x4){0.f, 0.f, 0.f, 0.f};
;         cur = nxt; cA = nA; cB = nB; ++ui;
.LBB0_1118:
	s_add_i32 s49, s49, 1
	s_mov_b64 s[2:3], s[28:29]
	s_mov_b32 s28, s8
	s_mov_b32 s51, s8
	s_mul_i32 s8, s49, s66
	s_add_i32 s54, s8, s14
	s_cmpk_lt_i32 s54, 0x100
	s_mov_b32 s29, s24
	s_mov_b32 s50, s24
	s_cselect_b64 s[42:43], -1, 0
	s_and_b32 s24, s54, 7
	s_ashr_i32 s8, s54, 3
	s_mov_b64 s[20:21], s[12:13]
	s_and_b64 s[12:13], s[42:43], exec
	s_cselect_b32 s13, s24, s29
	s_cselect_b32 s12, s8, s28
	s_ashr_i32 s28, s13, 1
	s_ashr_i32 s29, s28, 31
	s_lshl_b64 s[44:45], s[28:29], 10
	s_add_u32 s28, s16, s44
	s_addc_u32 s29, s17, s45
	s_ashr_i32 s13, s12, 31
	s_lshl_b64 s[12:13], s[12:13], 20
	s_add_u32 s28, s28, s12
	s_addc_u32 s29, s29, s13
	s_and_b64 s[12:13], s[42:43], exec
	s_cselect_b32 s52, s29, s3
	s_cselect_b32 s53, s28, s2
	s_lshl_b32 s12, s54, 20
	s_and_b32 s12, s12, 0x600000
	s_sub_u32 s12, s44, s12
	s_subb_u32 s13, s45, 0
	s_add_u32 s12, s18, s12
	s_addc_u32 s13, s22, s13
	s_lshl_b32 s44, s24, 20
	s_add_u32 s12, s12, s44
	s_addc_u32 s13, s13, 0
	s_and_b64 s[44:45], s[42:43], exec
	s_cselect_b32 s54, s13, s21
	s_cselect_b32 s55, s12, s20
	s_add_u32 s44, s2, 0x80080
	s_addc_u32 s45, s3, 0
	s_add_u32 s56, s20, 0x100
	v_mov_b64_e32 v[2:3], 0
	s_addc_u32 s57, s21, 0
	s_mov_b32 s58, -2
	v_mov_b64_e32 v[4:5], 0
	v_mov_b64_e32 v[6:7], 0
	v_mov_b64_e32 v[8:9], 0
	v_mov_b64_e32 v[10:11], 0
	v_mov_b64_e32 v[12:13], 0
	v_mov_b64_e32 v[14:15], 0
	v_mov_b64_e32 v[16:17], 0
	v_mov_b64_e32 v[18:19], 0
	v_mov_b64_e32 v[20:21], 0
	v_mov_b64_e32 v[22:23], 0
	v_mov_b64_e32 v[24:25], 0
	v_mov_b64_e32 v[26:27], 0
	v_mov_b64_e32 v[28:29], 0
	v_mov_b64_e32 v[30:31], 0
	v_mov_b64_e32 v[32:33], 0
	v_mov_b64_e32 v[34:35], 0
	v_mov_b64_e32 v[36:37], 0
	v_mov_b64_e32 v[38:39], 0
	v_mov_b64_e32 v[40:41], 0
	v_mov_b64_e32 v[42:43], 0
	v_mov_b64_e32 v[44:45], 0
	v_mov_b64_e32 v[46:47], 0
	v_mov_b64_e32 v[48:49], 0
	v_mov_b64_e32 v[50:51], 0
	v_mov_b64_e32 v[52:53], 0
	v_mov_b64_e32 v[54:55], 0
	v_mov_b64_e32 v[56:57], 0
	v_mov_b64_e32 v[58:59], 0
	v_mov_b64_e32 v[60:61], 0
	v_mov_b64_e32 v[62:63], 0
	v_mov_b64_e32 v[64:65], 0
	v_mov_b64_e32 v[66:67], 0
	v_mov_b64_e32 v[68:69], 0
	v_mov_b64_e32 v[70:71], 0
	v_mov_b64_e32 v[72:73], 0
	v_mov_b64_e32 v[74:75], 0
	v_mov_b64_e32 v[76:77], 0
	v_mov_b64_e32 v[78:79], 0
	v_mov_b64_e32 v[80:81], 0
	v_mov_b64_e32 v[82:83], 0
	v_mov_b64_e32 v[84:85], 0
	v_mov_b64_e32 v[86:87], 0
	v_mov_b64_e32 v[88:89], 0
	v_mov_b64_e32 v[90:91], 0
	v_mov_b64_e32 v[92:93], 0
	v_mov_b64_e32 v[94:95], 0
	v_mov_b64_e32 v[96:97], 0
	v_mov_b64_e32 v[98:99], 0
	v_mov_b64_e32 v[100:101], 0
	v_mov_b64_e32 v[102:103], 0
	v_mov_b64_e32 v[104:105], 0
	v_mov_b64_e32 v[106:107], 0
	v_mov_b64_e32 v[108:109], 0
	v_mov_b64_e32 v[110:111], 0
	v_mov_b64_e32 v[112:113], 0
	v_mov_b64_e32 v[114:115], 0
	v_mov_b64_e32 v[116:117], 0
	v_mov_b64_e32 v[118:119], 0
	v_mov_b64_e32 v[120:121], 0
	v_mov_b64_e32 v[122:123], 0
	v_mov_b64_e32 v[124:125], 0
	v_mov_b64_e32 v[126:127], 0
	v_mov_b64_e32 v[128:129], 0

; template <class Epi, class Sched, bool ALIGN_EPI = true, bool SP2 = true, bool GS = false>
; __device__ __forceinline__ void gemm_phase(PG8_LAS unsigned char* lds, const Gemm g, const Sched& S, const Epi& E, const float* gs_ss = nullptr) {
;     ...
; #pragma unroll
;         for (int a = 0; a < 2; ++a)
; #pragma unroll
;             for (int b = 0; b < 2; ++b)
; #pragma unroll
;                 for (int m = 0; m < 4; ++m)
; #pragma unroll
;                     for (int n = 0; n < 2; ++n) acc[a][b][m][n] = (f32x4){0.f, 0.f, 0.f, 0.f};
;         cur = nxt; cA = nA; cB = nB; ++ui;
.LBB0_1251:
	s_ashr_i32 s51, s50, 31
	s_lshl_b64 s[2:3], s[50:51], 18
	s_add_u32 s52, s16, s2
	s_addc_u32 s53, s17, s3
	s_and_b64 s[2:3], s[40:41], exec
	s_cselect_b32 s18, s53, s57
	s_cselect_b32 s51, s52, s56
	s_ashr_i32 s49, s48, 31
	s_lshl_b64 s[2:3], s[48:49], 18
	s_add_u32 s54, s22, s2
	s_addc_u32 s55, s23, s3
	s_and_b64 s[2:3], s[40:41], exec
	s_cselect_b32 s49, s55, s59
	s_cselect_b32 s63, s54, s58
	s_add_u32 s56, s56, 0x20080
	s_addc_u32 s57, s57, 0
	s_add_u32 s58, s58, 0x100
	v_mov_b64_e32 v[2:3], 0
	s_addc_u32 s59, s59, 0
	s_mov_b32 s64, -2
	v_mov_b64_e32 v[4:5], 0
	v_mov_b64_e32 v[6:7], 0
	v_mov_b64_e32 v[8:9], 0
	v_mov_b64_e32 v[10:11], 0
	v_mov_b64_e32 v[12:13], 0
	v_mov_b64_e32 v[14:15], 0
	v_mov_b64_e32 v[16:17], 0
	v_mov_b64_e32 v[18:19], 0
	v_mov_b64_e32 v[20:21], 0
	v_mov_b64_e32 v[22:23], 0
	v_mov_b64_e32 v[24:25], 0
	v_mov_b64_e32 v[26:27], 0
	v_mov_b64_e32 v[28:29], 0
	v_mov_b64_e32 v[30:31], 0
	v_mov_b64_e32 v[32:33], 0
	v_mov_b64_e32 v[34:35], 0
	v_mov_b64_e32 v[36:37], 0
	v_mov_b64_e32 v[38:39], 0
	v_mov_b64_e32 v[40:41], 0
	v_mov_b64_e32 v[42:43], 0
	v_mov_b64_e32 v[44:45], 0
	v_mov_b64_e32 v[46:47], 0
	v_mov_b64_e32 v[48:49], 0
	v_mov_b64_e32 v[50:51], 0
	v_mov_b64_e32 v[52:53], 0
	v_mov_b64_e32 v[54:55], 0
	v_mov_b64_e32 v[56:57], 0
	v_mov_b64_e32 v[58:59], 0
	v_mov_b64_e32 v[60:61], 0
	v_mov_b64_e32 v[62:63], 0
	v_mov_b64_e32 v[64:65], 0
	v_mov_b64_e32 v[66:67], 0
	v_mov_b64_e32 v[68:69], 0
	v_mov_b64_e32 v[70:71], 0
	v_mov_b64_e32 v[72:73], 0
	v_mov_b64_e32 v[74:75], 0
	v_mov_b64_e32 v[76:77], 0
	v_mov_b64_e32 v[78:79], 0
	v_mov_b64_e32 v[80:81], 0
	v_mov_b64_e32 v[82:83], 0
	v_mov_b64_e32 v[84:85], 0
	v_mov_b64_e32 v[86:87], 0
	v_mov_b64_e32 v[88:89], 0
	v_mov_b64_e32 v[90:91], 0
	v_mov_b64_e32 v[92:93], 0
	v_mov_b64_e32 v[94:95], 0
	v_mov_b64_e32 v[96:97], 0
	v_mov_b64_e32 v[98:99], 0
	v_mov_b64_e32 v[100:101], 0
	v_mov_b64_e32 v[102:103], 0
	v_mov_b64_e32 v[104:105], 0
	v_mov_b64_e32 v[106:107], 0
	v_mov_b64_e32 v[108:109], 0
	v_mov_b64_e32 v[110:111], 0
	v_mov_b64_e32 v[112:113], 0
	v_mov_b64_e32 v[114:115], 0
	v_mov_b64_e32 v[116:117], 0
	v_mov_b64_e32 v[118:119], 0
	v_mov_b64_e32 v[120:121], 0
	v_mov_b64_e32 v[126:127], 0
	v_mov_b64_e32 v[128:129], 0
	v_mov_b64_e32 v[134:135], 0
	v_mov_b64_e32 v[136:137], 0

; template <class Epi, class Sched, bool ALIGN_EPI = true, bool SP2 = true, bool GS = false>
; __device__ __forceinline__ void gemm_phase(PG8_LAS unsigned char* lds, const Gemm g, const Sched& S, const Epi& E, const float* gs_ss = nullptr) {
;     ...
; #pragma unroll
;         for (int a = 0; a < 2; ++a)
; #pragma unroll
;             for (int b = 0; b < 2; ++b)
; #pragma unroll
;                 for (int m = 0; m < 4; ++m)
; #pragma unroll
;                     for (int n = 0; n < 2; ++n) acc[a][b][m][n] = (f32x4){0.f, 0.f, 0.f, 0.f};
;         cur = nxt; cA = nA; cB = nB; ++ui;
.LBB0_1343:
	s_ashr_i32 s43, s42, 31
	s_lshl_b64 s[2:3], s[42:43], 20
	s_add_u32 s44, s17, s2
	s_addc_u32 s45, s22, s3
	s_and_b64 s[2:3], s[38:39], exec
	s_cselect_b32 s43, s45, s51
	s_cselect_b32 s57, s44, s50
	s_ashr_i32 s41, s40, 31
	s_lshl_b64 s[2:3], s[40:41], 20
	s_add_u32 s46, s23, s2
	s_addc_u32 s47, s24, s3
	s_and_b64 s[2:3], s[38:39], exec
	s_cselect_b32 s41, s47, s53
	s_cselect_b32 s58, s46, s52
	s_add_u32 s50, s50, 0x80080
	s_addc_u32 s51, s51, 0
	s_add_u32 s52, s52, 0x100
	v_mov_b64_e32 v[2:3], 0
	s_addc_u32 s53, s53, 0
	s_mov_b32 s59, -2
	v_mov_b64_e32 v[4:5], 0
	v_mov_b64_e32 v[6:7], 0
	v_mov_b64_e32 v[8:9], 0
	v_mov_b64_e32 v[10:11], 0
	v_mov_b64_e32 v[12:13], 0
	v_mov_b64_e32 v[14:15], 0
	v_mov_b64_e32 v[16:17], 0
	v_mov_b64_e32 v[18:19], 0
	v_mov_b64_e32 v[20:21], 0
	v_mov_b64_e32 v[22:23], 0
	v_mov_b64_e32 v[24:25], 0
	v_mov_b64_e32 v[26:27], 0
	v_mov_b64_e32 v[28:29], 0
	v_mov_b64_e32 v[30:31], 0
	v_mov_b64_e32 v[32:33], 0
	v_mov_b64_e32 v[34:35], 0
	v_mov_b64_e32 v[36:37], 0
	v_mov_b64_e32 v[38:39], 0
	v_mov_b64_e32 v[40:41], 0
	v_mov_b64_e32 v[42:43], 0
	v_mov_b64_e32 v[44:45], 0
	v_mov_b64_e32 v[46:47], 0
	v_mov_b64_e32 v[48:49], 0
	v_mov_b64_e32 v[50:51], 0
	v_mov_b64_e32 v[52:53], 0
	v_mov_b64_e32 v[54:55], 0
	v_mov_b64_e32 v[56:57], 0
	v_mov_b64_e32 v[58:59], 0
	v_mov_b64_e32 v[60:61], 0
	v_mov_b64_e32 v[62:63], 0
	v_mov_b64_e32 v[64:65], 0
	v_mov_b64_e32 v[66:67], 0
	v_mov_b64_e32 v[68:69], 0
	v_mov_b64_e32 v[70:71], 0
	v_mov_b64_e32 v[72:73], 0
	v_mov_b64_e32 v[74:75], 0
	v_mov_b64_e32 v[76:77], 0
	v_mov_b64_e32 v[78:79], 0
	v_mov_b64_e32 v[80:81], 0
	v_mov_b64_e32 v[82:83], 0
	v_mov_b64_e32 v[84:85], 0
	v_mov_b64_e32 v[86:87], 0
	v_mov_b64_e32 v[88:89], 0
	v_mov_b64_e32 v[90:91], 0
	v_mov_b64_e32 v[92:93], 0
	v_mov_b64_e32 v[94:95], 0
	v_mov_b64_e32 v[96:97], 0
	v_mov_b64_e32 v[98:99], 0
	v_mov_b64_e32 v[100:101], 0
	v_mov_b64_e32 v[102:103], 0
	v_mov_b64_e32 v[104:105], 0
	v_mov_b64_e32 v[106:107], 0
	v_mov_b64_e32 v[108:109], 0
	v_mov_b64_e32 v[110:111], 0
	v_mov_b64_e32 v[112:113], 0
	v_mov_b64_e32 v[114:115], 0
	v_mov_b64_e32 v[116:117], 0
	v_mov_b64_e32 v[118:119], 0
	v_mov_b64_e32 v[120:121], 0
	v_mov_b64_e32 v[122:123], 0
	v_mov_b64_e32 v[124:125], 0
	v_mov_b64_e32 v[126:127], 0
	v_mov_b64_e32 v[128:129], 0

; template <class Epi, class Sched, bool ALIGN_EPI = true, bool SP2 = true, bool GS = false>
; __device__ __forceinline__ void gemm_phase(PG8_LAS unsigned char* lds, const Gemm g, const Sched& S, const Epi& E, const float* gs_ss = nullptr) {
;     ...
; #pragma unroll
;         for (int a = 0; a < 2; ++a)
; #pragma unroll
;             for (int b = 0; b < 2; ++b)
; #pragma unroll
;                 for (int m = 0; m < 4; ++m)
; #pragma unroll
;                     for (int n = 0; n < 2; ++n) acc[a][b][m][n] = (f32x4){0.f, 0.f, 0.f, 0.f};
;         cur = nxt; cA = nA; cB = nB; ++ui;
.LBB0_1421:
	s_ashr_i32 s51, s50, 31
	s_lshl_b64 s[2:3], s[50:51], 22
	s_add_u32 s52, s16, s2
	s_addc_u32 s53, s17, s3
	s_and_b64 s[2:3], s[40:41], exec
	s_cselect_b32 s18, s53, s57
	s_cselect_b32 s51, s52, s56
	s_ashr_i32 s49, s48, 31
	s_lshl_b64 s[2:3], s[48:49], 22
	s_add_u32 s54, s22, s2
	s_addc_u32 s55, s23, s3
	s_and_b64 s[2:3], s[40:41], exec
	s_cselect_b32 s49, s55, s59
	s_cselect_b32 s63, s54, s58
	s_add_u32 s56, s56, 0x200080
	s_addc_u32 s57, s57, 0
	s_add_u32 s58, s58, 0x100
	v_mov_b64_e32 v[2:3], 0
	s_addc_u32 s59, s59, 0
	s_mov_b32 s64, -2
	v_mov_b64_e32 v[4:5], 0
	v_mov_b64_e32 v[6:7], 0
	v_mov_b64_e32 v[8:9], 0
	v_mov_b64_e32 v[10:11], 0
	v_mov_b64_e32 v[12:13], 0
	v_mov_b64_e32 v[14:15], 0
	v_mov_b64_e32 v[16:17], 0
	v_mov_b64_e32 v[18:19], 0
	v_mov_b64_e32 v[20:21], 0
	v_mov_b64_e32 v[22:23], 0
	v_mov_b64_e32 v[24:25], 0
	v_mov_b64_e32 v[26:27], 0
	v_mov_b64_e32 v[28:29], 0
	v_mov_b64_e32 v[30:31], 0
	v_mov_b64_e32 v[32:33], 0
	v_mov_b64_e32 v[34:35], 0
	v_mov_b64_e32 v[36:37], 0
	v_mov_b64_e32 v[38:39], 0
	v_mov_b64_e32 v[40:41], 0
	v_mov_b64_e32 v[42:43], 0
	v_mov_b64_e32 v[44:45], 0
	v_mov_b64_e32 v[46:47], 0
	v_mov_b64_e32 v[48:49], 0
	v_mov_b64_e32 v[50:51], 0
	v_mov_b64_e32 v[52:53], 0
	v_mov_b64_e32 v[54:55], 0
	v_mov_b64_e32 v[56:57], 0
	v_mov_b64_e32 v[58:59], 0
	v_mov_b64_e32 v[60:61], 0
	v_mov_b64_e32 v[62:63], 0
	v_mov_b64_e32 v[64:65], 0
	v_mov_b64_e32 v[66:67], 0
	v_mov_b64_e32 v[68:69], 0
	v_mov_b64_e32 v[70:71], 0
	v_mov_b64_e32 v[72:73], 0
	v_mov_b64_e32 v[74:75], 0
	v_mov_b64_e32 v[76:77], 0
	v_mov_b64_e32 v[78:79], 0
	v_mov_b64_e32 v[80:81], 0
	v_mov_b64_e32 v[82:83], 0
	v_mov_b64_e32 v[84:85], 0
	v_mov_b64_e32 v[86:87], 0
	v_mov_b64_e32 v[88:89], 0
	v_mov_b64_e32 v[90:91], 0
	v_mov_b64_e32 v[92:93], 0
	v_mov_b64_e32 v[94:95], 0
	v_mov_b64_e32 v[96:97], 0
	v_mov_b64_e32 v[98:99], 0
	v_mov_b64_e32 v[100:101], 0
	v_mov_b64_e32 v[102:103], 0
	v_mov_b64_e32 v[104:105], 0
	v_mov_b64_e32 v[106:107], 0
	v_mov_b64_e32 v[108:109], 0
	v_mov_b64_e32 v[110:111], 0
	v_mov_b64_e32 v[112:113], 0
	v_mov_b64_e32 v[114:115], 0
	v_mov_b64_e32 v[116:117], 0
	v_mov_b64_e32 v[118:119], 0
	v_mov_b64_e32 v[120:121], 0
	v_mov_b64_e32 v[122:123], 0
	v_mov_b64_e32 v[124:125], 0
	v_mov_b64_e32 v[126:127], 0
	v_mov_b64_e32 v[128:129], 0
